# indexer selection mask: per key a 64-bit (key,index) borrow chain v_cmp/v_subb/v_addc on four interleaved carry registers replaces three compares + SALU + cndmask + shift
# speedup vs baseline: 1.0053x; 1.0053x over previous
; __device__ __forceinline__ void sel_unit(LAS char* lds, int b, int u, const bf16_t* QI, const bf16_t* KIDX, const float* WIDX, unsigned long long* MASK) {
;     ...
;     const int tid2 = opaque_tid(), kg2 = (tid2 & 63) >> 4; const size_t gq2 = rowbase + q0 + (tid2 & 15);
; #pragma unroll
;     for (int j = 0; j < 8; ++j) if (j < nj) {
;         const int t = SEL_TILE(j);
;         unsigned lo = 0u, hi = 0u;
; #pragma unroll
;         for (int kb = 0; kb < 4; ++kb)
; #pragma unroll
;             for (int i = 0; i < 4; ++i) { const unsigned k = sc[j][kb][i]; const unsigned kin = 16 * kb + 4 * kg2 + i;
;                 const unsigned v = 4095u - (unsigned)(64 * t + kin);
;                 const unsigned s = ((k > kstar) || (k == kstar && v >= vthr)) ? 1u : 0u;
;                 if (kb < 2) lo |= s << kin; else hi |= s << (kin - 32); __builtin_amdgcn_sched_barrier(0); }
;         { auto r = __builtin_amdgcn_permlane32_swap(lo, lo, false, false); lo = r[0] | r[1]; r = __builtin_amdgcn_permlane16_swap(lo, lo, false, false); lo = r[0] | r[1];
;           r = __builtin_amdgcn_permlane32_swap(hi, hi, false, false); hi = r[0] | r[1]; r = __builtin_amdgcn_permlane16_swap(hi, hi, false, false); hi = r[0] | r[1]; }
;         if (kg2 == 0) MASK[gq2 * 64 + t] = ((unsigned long long)hi << 32) | lo;
;     }
.LBB0_1070:
	s_getreg_b32 s0, hwreg(HW_REG_HW_ID, 0, 6)
	s_lshl_b32 s0, s0, 2
	s_and_b32 s0, s0, 0xfc
	s_add_i32 s0, s0, 0x20040
	v_mov_b32_e32 v2, s0
	ds_read_b32 v2, v2
	s_waitcnt lgkmcnt(0)
	v_mov_b32_e32 v2, v1
	v_mov_b32_e32 v3, s53
	v_mbcnt_lo_u32_b32 v2, -1, v2
	v_mbcnt_hi_u32_b32 v2, -1, v2
	v_bfe_u32 v4, v2, 4, 2
	v_and_or_b32 v2, v2, 15, s52
	v_lshlrev_b32_e32 v20, 2, v4
	v_lshlrev_b64 v[2:3], 9, v[2:3]
	v_cmp_eq_u32_e64 s[16:17], 0, v4
	v_lshl_add_u64 v[2:3], s[68:69], 0, v[2:3]
	s_andn2_b64 vcc, exec, s[22:23]
	v_or_b32_e32 v19, 1, v20
	v_or_b32_e32 v9, 2, v20
	v_or_b32_e32 v8, 3, v20
	v_or_b32_e32 v7, 16, v20
	v_or_b32_e32 v6, 17, v20
	v_or_b32_e32 v5, 18, v20
	v_or_b32_e32 v4, 19, v20
	s_cbranch_vccnz .LBB0_1074
	s_lshl_b32 s21, s46, 6
	s_sub_i32 s21, 0xfff, s21
	v_sub_u32_e32 v21, s21, v20
	v_sub_u32_e32 v21, v21, v0
	v_cmp_gt_i32_e64 vcc, 3, v21
	v_cmp_gt_i32_e64 s[0:1], 19, v21
	v_cmp_gt_i32_e64 s[18:19], 35, v21
	v_cmp_gt_i32_e64 s[22:23], 51, v21
	v_subb_co_u32_e64 v26, vcc, v63, v18, vcc
	v_subb_co_u32_e64 v27, s[0:1], v67, v18, s[0:1]
	v_subb_co_u32_e64 v28, s[18:19], v71, v18, s[18:19]
	v_subb_co_u32_e64 v29, s[22:23], v75, v18, s[22:23]
	v_addc_co_u32_e64 v22, vcc, 0, 0, vcc
	v_addc_co_u32_e64 v23, s[0:1], 0, 0, s[0:1]
	v_addc_co_u32_e64 v24, s[18:19], 0, 0, s[18:19]
	v_addc_co_u32_e64 v25, s[22:23], 0, 0, s[22:23]
	v_cmp_gt_i32_e64 vcc, 2, v21
	v_cmp_gt_i32_e64 s[0:1], 18, v21
	v_cmp_gt_i32_e64 s[18:19], 34, v21
	v_cmp_gt_i32_e64 s[22:23], 50, v21
	v_subb_co_u32_e64 v26, vcc, v64, v18, vcc
	v_subb_co_u32_e64 v27, s[0:1], v68, v18, s[0:1]
	v_subb_co_u32_e64 v28, s[18:19], v72, v18, s[18:19]
	v_subb_co_u32_e64 v29, s[22:23], v76, v18, s[22:23]
	v_addc_co_u32_e64 v22, vcc, v22, v22, vcc
	v_addc_co_u32_e64 v23, s[0:1], v23, v23, s[0:1]
	v_addc_co_u32_e64 v24, s[18:19], v24, v24, s[18:19]
	v_addc_co_u32_e64 v25, s[22:23], v25, v25, s[22:23]
	v_cmp_gt_i32_e64 vcc, 1, v21
	v_cmp_gt_i32_e64 s[0:1], 17, v21
	v_cmp_gt_i32_e64 s[18:19], 33, v21
	v_cmp_gt_i32_e64 s[22:23], 49, v21
	v_subb_co_u32_e64 v26, vcc, v61, v18, vcc
	v_subb_co_u32_e64 v27, s[0:1], v65, v18, s[0:1]
	v_subb_co_u32_e64 v28, s[18:19], v69, v18, s[18:19]
	v_subb_co_u32_e64 v29, s[22:23], v73, v18, s[22:23]
	v_addc_co_u32_e64 v22, vcc, v22, v22, vcc
	v_addc_co_u32_e64 v23, s[0:1], v23, v23, s[0:1]
	v_addc_co_u32_e64 v24, s[18:19], v24, v24, s[18:19]
	v_addc_co_u32_e64 v25, s[22:23], v25, v25, s[22:23]
	v_cmp_gt_i32_e64 vcc, 0, v21
	v_cmp_gt_i32_e64 s[0:1], 16, v21
	v_cmp_gt_i32_e64 s[18:19], 32, v21
	v_cmp_gt_i32_e64 s[22:23], 48, v21
	v_subb_co_u32_e64 v26, vcc, v62, v18, vcc
	v_subb_co_u32_e64 v27, s[0:1], v66, v18, s[0:1]
	v_subb_co_u32_e64 v28, s[18:19], v70, v18, s[18:19]
	v_subb_co_u32_e64 v29, s[22:23], v74, v18, s[22:23]
	v_addc_co_u32_e64 v22, vcc, v22, v22, vcc
	v_addc_co_u32_e64 v23, s[0:1], v23, v23, s[0:1]
	v_addc_co_u32_e64 v24, s[18:19], v24, v24, s[18:19]
	v_addc_co_u32_e64 v25, s[22:23], v25, v25, s[22:23]
	v_lshlrev_b32_e32 v34, v20, v22
	v_lshlrev_b32_e32 v35, v20, v24
	v_lshl_or_b32 v34, v23, v7, v34
	v_lshl_or_b32 v35, v25, v7, v35
	s_nop 0
	v_mov_b32_e32 v36, v34
	v_mov_b32_e32 v37, v35
	s_nop 1
	v_permlane32_swap_b32_e32 v34, v36
	v_permlane32_swap_b32_e32 v35, v37
	v_or_b32_e32 v34, v34, v36
	v_or_b32_e32 v35, v35, v37
	v_mov_b32_e32 v36, v34
	v_mov_b32_e32 v37, v35
	s_nop 1
	v_permlane16_swap_b32_e32 v34, v36
	v_permlane16_swap_b32_e32 v35, v37
	v_or_b32_e32 v34, v34, v36
	v_or_b32_e32 v35, v35, v37
	v_not_b32_e32 v34, v34
	v_not_b32_e32 v35, v35
	s_ashr_i32 s47, s46, 31
	s_and_saveexec_b64 s[0:1], s[16:17]
	v_lshl_add_u64 v[32:33], s[46:47], 3, v[2:3]
	global_store_dwordx2 v[32:33], v[34:35], off
	s_or_b64 exec, exec, s[0:1]
.LBB0_1074:
	s_and_b64 vcc, exec, s[2:3]
	s_cbranch_vccnz .LBB0_1087
	s_lshl_b32 s21, s46, 6
	s_sub_i32 s21, 0xdff, s21
	v_sub_u32_e32 v21, s21, v20
	v_sub_u32_e32 v21, v21, v0
	v_cmp_gt_i32_e64 vcc, 3, v21
	v_cmp_gt_i32_e64 s[0:1], 19, v21
	v_cmp_gt_i32_e64 s[18:19], 35, v21
	v_cmp_gt_i32_e64 s[22:23], 51, v21
	v_subb_co_u32_e64 v26, vcc, v79, v18, vcc
	v_subb_co_u32_e64 v27, s[0:1], v83, v18, s[0:1]
	v_subb_co_u32_e64 v28, s[18:19], v87, v18, s[18:19]
	v_subb_co_u32_e64 v29, s[22:23], v91, v18, s[22:23]
	v_addc_co_u32_e64 v22, vcc, 0, 0, vcc
	v_addc_co_u32_e64 v23, s[0:1], 0, 0, s[0:1]
	v_addc_co_u32_e64 v24, s[18:19], 0, 0, s[18:19]
	v_addc_co_u32_e64 v25, s[22:23], 0, 0, s[22:23]
	v_cmp_gt_i32_e64 vcc, 2, v21
	v_cmp_gt_i32_e64 s[0:1], 18, v21
	v_cmp_gt_i32_e64 s[18:19], 34, v21
	v_cmp_gt_i32_e64 s[22:23], 50, v21
	v_subb_co_u32_e64 v26, vcc, v80, v18, vcc
	v_subb_co_u32_e64 v27, s[0:1], v84, v18, s[0:1]
	v_subb_co_u32_e64 v28, s[18:19], v88, v18, s[18:19]
	v_subb_co_u32_e64 v29, s[22:23], v92, v18, s[22:23]
	v_addc_co_u32_e64 v22, vcc, v22, v22, vcc
	v_addc_co_u32_e64 v23, s[0:1], v23, v23, s[0:1]
	v_addc_co_u32_e64 v24, s[18:19], v24, v24, s[18:19]
	v_addc_co_u32_e64 v25, s[22:23], v25, v25, s[22:23]
	v_cmp_gt_i32_e64 vcc, 1, v21
	v_cmp_gt_i32_e64 s[0:1], 17, v21
	v_cmp_gt_i32_e64 s[18:19], 33, v21
	v_cmp_gt_i32_e64 s[22:23], 49, v21
	v_subb_co_u32_e64 v26, vcc, v77, v18, vcc
	v_subb_co_u32_e64 v27, s[0:1], v81, v18, s[0:1]
	v_subb_co_u32_e64 v28, s[18:19], v85, v18, s[18:19]
	v_subb_co_u32_e64 v29, s[22:23], v89, v18, s[22:23]
	v_addc_co_u32_e64 v22, vcc, v22, v22, vcc
	v_addc_co_u32_e64 v23, s[0:1], v23, v23, s[0:1]
	v_addc_co_u32_e64 v24, s[18:19], v24, v24, s[18:19]
	v_addc_co_u32_e64 v25, s[22:23], v25, v25, s[22:23]
	v_cmp_gt_i32_e64 vcc, 0, v21
	v_cmp_gt_i32_e64 s[0:1], 16, v21
	v_cmp_gt_i32_e64 s[18:19], 32, v21
	v_cmp_gt_i32_e64 s[22:23], 48, v21
	v_subb_co_u32_e64 v26, vcc, v78, v18, vcc
	v_subb_co_u32_e64 v27, s[0:1], v82, v18, s[0:1]
	v_subb_co_u32_e64 v28, s[18:19], v86, v18, s[18:19]
	v_subb_co_u32_e64 v29, s[22:23], v90, v18, s[22:23]
	v_addc_co_u32_e64 v22, vcc, v22, v22, vcc
	v_addc_co_u32_e64 v23, s[0:1], v23, v23, s[0:1]
	v_addc_co_u32_e64 v24, s[18:19], v24, v24, s[18:19]
	v_addc_co_u32_e64 v25, s[22:23], v25, v25, s[22:23]
	v_lshlrev_b32_e32 v34, v20, v22
	v_lshlrev_b32_e32 v35, v20, v24
	v_lshl_or_b32 v34, v23, v7, v34
	v_lshl_or_b32 v35, v25, v7, v35
	s_nop 0
	v_mov_b32_e32 v36, v34
	v_mov_b32_e32 v37, v35
	s_nop 1
	v_permlane32_swap_b32_e32 v34, v36
	v_permlane32_swap_b32_e32 v35, v37
	v_or_b32_e32 v34, v34, v36
	v_or_b32_e32 v35, v35, v37
	v_mov_b32_e32 v36, v34
	v_mov_b32_e32 v37, v35
	s_nop 1
	v_permlane16_swap_b32_e32 v34, v36
	v_permlane16_swap_b32_e32 v35, v37
	v_or_b32_e32 v34, v34, v36
	v_or_b32_e32 v35, v35, v37
	v_not_b32_e32 v34, v34
	v_not_b32_e32 v35, v35
	s_ashr_i32 s47, s46, 31
	s_and_saveexec_b64 s[0:1], s[16:17]
	v_lshl_add_u64 v[32:33], s[46:47], 3, v[2:3]
	global_store_dwordx2 v[32:33], v[34:35], off offset:64
	s_or_b64 exec, exec, s[0:1]
	s_and_b64 vcc, exec, s[4:5]
	s_cbranch_vccz .LBB0_1088

; __device__ __forceinline__ void sel_unit(LAS char* lds, int b, int u, const bf16_t* QI, const bf16_t* KIDX, const float* WIDX, unsigned long long* MASK) {
;     ...
;     for (int j = 0; j < 8; ++j) if (j < nj) {
;         const int t = SEL_TILE(j);
;         unsigned lo = 0u, hi = 0u;
; #pragma unroll
;         for (int kb = 0; kb < 4; ++kb)
; #pragma unroll
;             for (int i = 0; i < 4; ++i) { const unsigned k = sc[j][kb][i]; const unsigned kin = 16 * kb + 4 * kg2 + i;
;                 const unsigned v = 4095u - (unsigned)(64 * t + kin);
;                 const unsigned s = ((k > kstar) || (k == kstar && v >= vthr)) ? 1u : 0u;
;                 if (kb < 2) lo |= s << kin; else hi |= s << (kin - 32); __builtin_amdgcn_sched_barrier(0); }
;         { auto r = __builtin_amdgcn_permlane32_swap(lo, lo, false, false); lo = r[0] | r[1]; r = __builtin_amdgcn_permlane16_swap(lo, lo, false, false); lo = r[0] | r[1];
;           r = __builtin_amdgcn_permlane32_swap(hi, hi, false, false); hi = r[0] | r[1]; r = __builtin_amdgcn_permlane16_swap(hi, hi, false, false); hi = r[0] | r[1]; }
;         if (kg2 == 0) MASK[gq2 * 64 + t] = ((unsigned long long)hi << 32) | lo;
.LBB0_1079:
	s_lshl_b32 s21, s46, 6
	s_sub_i32 s21, 0x9ff, s21
	v_sub_u32_e32 v21, s21, v20
	v_sub_u32_e32 v21, v21, v0
	v_cmp_gt_i32_e64 vcc, 3, v21
	v_cmp_gt_i32_e64 s[0:1], 19, v21
	v_cmp_gt_i32_e64 s[18:19], 35, v21
	v_cmp_gt_i32_e64 s[22:23], 51, v21
	v_subb_co_u32_e64 v26, vcc, v111, v18, vcc
	v_subb_co_u32_e64 v27, s[0:1], v115, v18, s[0:1]
	v_subb_co_u32_e64 v28, s[18:19], v119, v18, s[18:19]
	v_subb_co_u32_e64 v29, s[22:23], v123, v18, s[22:23]
	v_addc_co_u32_e64 v22, vcc, 0, 0, vcc
	v_addc_co_u32_e64 v23, s[0:1], 0, 0, s[0:1]
	v_addc_co_u32_e64 v24, s[18:19], 0, 0, s[18:19]
	v_addc_co_u32_e64 v25, s[22:23], 0, 0, s[22:23]
	v_cmp_gt_i32_e64 vcc, 2, v21
	v_cmp_gt_i32_e64 s[0:1], 18, v21
	v_cmp_gt_i32_e64 s[18:19], 34, v21
	v_cmp_gt_i32_e64 s[22:23], 50, v21
	v_subb_co_u32_e64 v26, vcc, v112, v18, vcc
	v_subb_co_u32_e64 v27, s[0:1], v116, v18, s[0:1]
	v_subb_co_u32_e64 v28, s[18:19], v120, v18, s[18:19]
	v_subb_co_u32_e64 v29, s[22:23], v124, v18, s[22:23]
	v_addc_co_u32_e64 v22, vcc, v22, v22, vcc
	v_addc_co_u32_e64 v23, s[0:1], v23, v23, s[0:1]
	v_addc_co_u32_e64 v24, s[18:19], v24, v24, s[18:19]
	v_addc_co_u32_e64 v25, s[22:23], v25, v25, s[22:23]
	v_cmp_gt_i32_e64 vcc, 1, v21
	v_cmp_gt_i32_e64 s[0:1], 17, v21
	v_cmp_gt_i32_e64 s[18:19], 33, v21
	v_cmp_gt_i32_e64 s[22:23], 49, v21
	v_subb_co_u32_e64 v26, vcc, v109, v18, vcc
	v_subb_co_u32_e64 v27, s[0:1], v113, v18, s[0:1]
	v_subb_co_u32_e64 v28, s[18:19], v117, v18, s[18:19]
	v_subb_co_u32_e64 v29, s[22:23], v121, v18, s[22:23]
	v_addc_co_u32_e64 v22, vcc, v22, v22, vcc
	v_addc_co_u32_e64 v23, s[0:1], v23, v23, s[0:1]
	v_addc_co_u32_e64 v24, s[18:19], v24, v24, s[18:19]
	v_addc_co_u32_e64 v25, s[22:23], v25, v25, s[22:23]
	v_cmp_gt_i32_e64 vcc, 0, v21
	v_cmp_gt_i32_e64 s[0:1], 16, v21
	v_cmp_gt_i32_e64 s[18:19], 32, v21
	v_cmp_gt_i32_e64 s[22:23], 48, v21
	v_subb_co_u32_e64 v26, vcc, v110, v18, vcc
	v_subb_co_u32_e64 v27, s[0:1], v114, v18, s[0:1]
	v_subb_co_u32_e64 v28, s[18:19], v118, v18, s[18:19]
	v_subb_co_u32_e64 v29, s[22:23], v122, v18, s[22:23]
	v_addc_co_u32_e64 v22, vcc, v22, v22, vcc
	v_addc_co_u32_e64 v23, s[0:1], v23, v23, s[0:1]
	v_addc_co_u32_e64 v24, s[18:19], v24, v24, s[18:19]
	v_addc_co_u32_e64 v25, s[22:23], v25, v25, s[22:23]
	v_lshlrev_b32_e32 v34, v20, v22
	v_lshlrev_b32_e32 v35, v20, v24
	v_lshl_or_b32 v34, v23, v7, v34
	v_lshl_or_b32 v35, v25, v7, v35
	s_nop 0
	v_mov_b32_e32 v36, v34
	v_mov_b32_e32 v37, v35
	s_nop 1
	v_permlane32_swap_b32_e32 v34, v36
	v_permlane32_swap_b32_e32 v35, v37
	v_or_b32_e32 v34, v34, v36
	v_or_b32_e32 v35, v35, v37
	v_mov_b32_e32 v36, v34
	v_mov_b32_e32 v37, v35
	s_nop 1
	v_permlane16_swap_b32_e32 v34, v36
	v_permlane16_swap_b32_e32 v35, v37
	v_or_b32_e32 v34, v34, v36
	v_or_b32_e32 v35, v35, v37
	v_not_b32_e32 v34, v34
	v_not_b32_e32 v35, v35
	s_ashr_i32 s47, s46, 31
	s_and_saveexec_b64 s[0:1], s[16:17]
	v_lshl_add_u64 v[32:33], s[46:47], 3, v[2:3]
	global_store_dwordx2 v[32:33], v[34:35], off offset:192
	s_or_b64 exec, exec, s[0:1]
	s_and_b64 vcc, exec, s[8:9]
	s_cbranch_vccz .LBB0_1092

; __device__ __forceinline__ void sel_unit(LAS char* lds, int b, int u, const bf16_t* QI, const bf16_t* KIDX, const float* WIDX, unsigned long long* MASK) {
;     ...
;     for (int j = 0; j < 8; ++j) if (j < nj) {
;         const int t = SEL_TILE(j);
;         unsigned lo = 0u, hi = 0u;
; #pragma unroll
;         for (int kb = 0; kb < 4; ++kb)
; #pragma unroll
;             for (int i = 0; i < 4; ++i) { const unsigned k = sc[j][kb][i]; const unsigned kin = 16 * kb + 4 * kg2 + i;
;                 const unsigned v = 4095u - (unsigned)(64 * t + kin);
;                 const unsigned s = ((k > kstar) || (k == kstar && v >= vthr)) ? 1u : 0u;
;                 if (kb < 2) lo |= s << kin; else hi |= s << (kin - 32); __builtin_amdgcn_sched_barrier(0); }
;         { auto r = __builtin_amdgcn_permlane32_swap(lo, lo, false, false); lo = r[0] | r[1]; r = __builtin_amdgcn_permlane16_swap(lo, lo, false, false); lo = r[0] | r[1];
;           r = __builtin_amdgcn_permlane32_swap(hi, hi, false, false); hi = r[0] | r[1]; r = __builtin_amdgcn_permlane16_swap(hi, hi, false, false); hi = r[0] | r[1]; }
;         if (kg2 == 0) MASK[gq2 * 64 + t] = ((unsigned long long)hi << 32) | lo;
.LBB0_1083:
	s_lshl_b32 s21, s46, 6
	s_sub_i32 s21, 0x5ff, s21
	v_sub_u32_e32 v21, s21, v20
	v_sub_u32_e32 v21, v21, v0
	v_cmp_gt_i32_e64 vcc, 3, v21
	v_cmp_gt_i32_e64 s[0:1], 19, v21
	v_cmp_gt_i32_e64 s[18:19], 35, v21
	v_cmp_gt_i32_e64 s[22:23], 51, v21
	v_subb_co_u32_e64 v26, vcc, v144, v18, vcc
	v_subb_co_u32_e64 v27, s[0:1], v148, v18, s[0:1]
	v_subb_co_u32_e64 v28, s[18:19], v181, v18, s[18:19]
	v_subb_co_u32_e64 v29, s[22:23], v189, v18, s[22:23]
	v_addc_co_u32_e64 v22, vcc, 0, 0, vcc
	v_addc_co_u32_e64 v23, s[0:1], 0, 0, s[0:1]
	v_addc_co_u32_e64 v24, s[18:19], 0, 0, s[18:19]
	v_addc_co_u32_e64 v25, s[22:23], 0, 0, s[22:23]
	v_cmp_gt_i32_e64 vcc, 2, v21
	v_cmp_gt_i32_e64 s[0:1], 18, v21
	v_cmp_gt_i32_e64 s[18:19], 34, v21
	v_cmp_gt_i32_e64 s[22:23], 50, v21
	v_subb_co_u32_e64 v26, vcc, v145, v18, vcc
	v_subb_co_u32_e64 v27, s[0:1], v149, v18, s[0:1]
	v_subb_co_u32_e64 v28, s[18:19], v186, v18, s[18:19]
	v_subb_co_u32_e64 v29, s[22:23], v190, v18, s[22:23]
	v_addc_co_u32_e64 v22, vcc, v22, v22, vcc
	v_addc_co_u32_e64 v23, s[0:1], v23, v23, s[0:1]
	v_addc_co_u32_e64 v24, s[18:19], v24, v24, s[18:19]
	v_addc_co_u32_e64 v25, s[22:23], v25, v25, s[22:23]
	v_cmp_gt_i32_e64 vcc, 1, v21
	v_cmp_gt_i32_e64 s[0:1], 17, v21
	v_cmp_gt_i32_e64 s[18:19], 33, v21
	v_cmp_gt_i32_e64 s[22:23], 49, v21
	v_subb_co_u32_e64 v26, vcc, v142, v18, vcc
	v_subb_co_u32_e64 v27, s[0:1], v146, v18, s[0:1]
	v_subb_co_u32_e64 v28, s[18:19], v177, v18, s[18:19]
	v_subb_co_u32_e64 v29, s[22:23], v187, v18, s[22:23]
	v_addc_co_u32_e64 v22, vcc, v22, v22, vcc
	v_addc_co_u32_e64 v23, s[0:1], v23, v23, s[0:1]
	v_addc_co_u32_e64 v24, s[18:19], v24, v24, s[18:19]
	v_addc_co_u32_e64 v25, s[22:23], v25, v25, s[22:23]
	v_cmp_gt_i32_e64 vcc, 0, v21
	v_cmp_gt_i32_e64 s[0:1], 16, v21
	v_cmp_gt_i32_e64 s[18:19], 32, v21
	v_cmp_gt_i32_e64 s[22:23], 48, v21
	v_subb_co_u32_e64 v26, vcc, v143, v18, vcc
	v_subb_co_u32_e64 v27, s[0:1], v147, v18, s[0:1]
	v_subb_co_u32_e64 v28, s[18:19], v178, v18, s[18:19]
	v_subb_co_u32_e64 v29, s[22:23], v188, v18, s[22:23]
	v_addc_co_u32_e64 v22, vcc, v22, v22, vcc
	v_addc_co_u32_e64 v23, s[0:1], v23, v23, s[0:1]
	v_addc_co_u32_e64 v24, s[18:19], v24, v24, s[18:19]
	v_addc_co_u32_e64 v25, s[22:23], v25, v25, s[22:23]
	v_lshlrev_b32_e32 v34, v20, v22
	v_lshlrev_b32_e32 v35, v20, v24
	v_lshl_or_b32 v34, v23, v7, v34
	v_lshl_or_b32 v35, v25, v7, v35
	s_nop 0
	v_mov_b32_e32 v36, v34
	v_mov_b32_e32 v37, v35
	s_nop 1
	v_permlane32_swap_b32_e32 v34, v36
	v_permlane32_swap_b32_e32 v35, v37
	v_or_b32_e32 v34, v34, v36
	v_or_b32_e32 v35, v35, v37
	v_mov_b32_e32 v36, v34
	v_mov_b32_e32 v37, v35
	s_nop 1
	v_permlane16_swap_b32_e32 v34, v36
	v_permlane16_swap_b32_e32 v35, v37
	v_or_b32_e32 v34, v34, v36
	v_or_b32_e32 v35, v35, v37
	v_not_b32_e32 v34, v34
	v_not_b32_e32 v35, v35
	s_ashr_i32 s47, s46, 31
	s_and_saveexec_b64 s[0:1], s[16:17]
	v_lshl_add_u64 v[32:33], s[46:47], 3, v[2:3]
	global_store_dwordx2 v[32:33], v[34:35], off offset:320
	s_or_b64 exec, exec, s[0:1]
	s_and_b64 vcc, exec, s[12:13]
	s_cbranch_vccz .LBB0_1096

; __device__ __forceinline__ void sel_unit(LAS char* lds, int b, int u, const bf16_t* QI, const bf16_t* KIDX, const float* WIDX, unsigned long long* MASK) {
;     ...
;     for (int j = 0; j < 8; ++j) if (j < nj) {
;         const int t = SEL_TILE(j);
;         unsigned lo = 0u, hi = 0u;
; #pragma unroll
;         for (int kb = 0; kb < 4; ++kb)
; #pragma unroll
;             for (int i = 0; i < 4; ++i) { const unsigned k = sc[j][kb][i]; const unsigned kin = 16 * kb + 4 * kg2 + i;
;                 const unsigned v = 4095u - (unsigned)(64 * t + kin);
;                 const unsigned s = ((k > kstar) || (k == kstar && v >= vthr)) ? 1u : 0u;
;                 if (kb < 2) lo |= s << kin; else hi |= s << (kin - 32); __builtin_amdgcn_sched_barrier(0); }
;         { auto r = __builtin_amdgcn_permlane32_swap(lo, lo, false, false); lo = r[0] | r[1]; r = __builtin_amdgcn_permlane16_swap(lo, lo, false, false); lo = r[0] | r[1];
;           r = __builtin_amdgcn_permlane32_swap(hi, hi, false, false); hi = r[0] | r[1]; r = __builtin_amdgcn_permlane16_swap(hi, hi, false, false); hi = r[0] | r[1]; }
;         if (kg2 == 0) MASK[gq2 * 64 + t] = ((unsigned long long)hi << 32) | lo;
.LBB0_1088:
	s_lshl_b32 s21, s46, 6
	s_sub_i32 s21, 0xbff, s21
	v_sub_u32_e32 v21, s21, v20
	v_sub_u32_e32 v21, v21, v0
	v_cmp_gt_i32_e64 vcc, 3, v21
	v_cmp_gt_i32_e64 s[0:1], 19, v21
	v_cmp_gt_i32_e64 s[18:19], 35, v21
	v_cmp_gt_i32_e64 s[22:23], 51, v21
	v_subb_co_u32_e64 v26, vcc, v95, v18, vcc
	v_subb_co_u32_e64 v27, s[0:1], v99, v18, s[0:1]
	v_subb_co_u32_e64 v28, s[18:19], v103, v18, s[18:19]
	v_subb_co_u32_e64 v29, s[22:23], v107, v18, s[22:23]
	v_addc_co_u32_e64 v22, vcc, 0, 0, vcc
	v_addc_co_u32_e64 v23, s[0:1], 0, 0, s[0:1]
	v_addc_co_u32_e64 v24, s[18:19], 0, 0, s[18:19]
	v_addc_co_u32_e64 v25, s[22:23], 0, 0, s[22:23]
	v_cmp_gt_i32_e64 vcc, 2, v21
	v_cmp_gt_i32_e64 s[0:1], 18, v21
	v_cmp_gt_i32_e64 s[18:19], 34, v21
	v_cmp_gt_i32_e64 s[22:23], 50, v21
	v_subb_co_u32_e64 v26, vcc, v96, v18, vcc
	v_subb_co_u32_e64 v27, s[0:1], v100, v18, s[0:1]
	v_subb_co_u32_e64 v28, s[18:19], v104, v18, s[18:19]
	v_subb_co_u32_e64 v29, s[22:23], v108, v18, s[22:23]
	v_addc_co_u32_e64 v22, vcc, v22, v22, vcc
	v_addc_co_u32_e64 v23, s[0:1], v23, v23, s[0:1]
	v_addc_co_u32_e64 v24, s[18:19], v24, v24, s[18:19]
	v_addc_co_u32_e64 v25, s[22:23], v25, v25, s[22:23]
	v_cmp_gt_i32_e64 vcc, 1, v21
	v_cmp_gt_i32_e64 s[0:1], 17, v21
	v_cmp_gt_i32_e64 s[18:19], 33, v21
	v_cmp_gt_i32_e64 s[22:23], 49, v21
	v_subb_co_u32_e64 v26, vcc, v93, v18, vcc
	v_subb_co_u32_e64 v27, s[0:1], v97, v18, s[0:1]
	v_subb_co_u32_e64 v28, s[18:19], v101, v18, s[18:19]
	v_subb_co_u32_e64 v29, s[22:23], v105, v18, s[22:23]
	v_addc_co_u32_e64 v22, vcc, v22, v22, vcc
	v_addc_co_u32_e64 v23, s[0:1], v23, v23, s[0:1]
	v_addc_co_u32_e64 v24, s[18:19], v24, v24, s[18:19]
	v_addc_co_u32_e64 v25, s[22:23], v25, v25, s[22:23]
	v_cmp_gt_i32_e64 vcc, 0, v21
	v_cmp_gt_i32_e64 s[0:1], 16, v21
	v_cmp_gt_i32_e64 s[18:19], 32, v21
	v_cmp_gt_i32_e64 s[22:23], 48, v21
	v_subb_co_u32_e64 v26, vcc, v94, v18, vcc
	v_subb_co_u32_e64 v27, s[0:1], v98, v18, s[0:1]
	v_subb_co_u32_e64 v28, s[18:19], v102, v18, s[18:19]
	v_subb_co_u32_e64 v29, s[22:23], v106, v18, s[22:23]
	v_addc_co_u32_e64 v22, vcc, v22, v22, vcc
	v_addc_co_u32_e64 v23, s[0:1], v23, v23, s[0:1]
	v_addc_co_u32_e64 v24, s[18:19], v24, v24, s[18:19]
	v_addc_co_u32_e64 v25, s[22:23], v25, v25, s[22:23]
	v_lshlrev_b32_e32 v34, v20, v22
	v_lshlrev_b32_e32 v35, v20, v24
	v_lshl_or_b32 v34, v23, v7, v34
	v_lshl_or_b32 v35, v25, v7, v35
	s_nop 0
	v_mov_b32_e32 v36, v34
	v_mov_b32_e32 v37, v35
	s_nop 1
	v_permlane32_swap_b32_e32 v34, v36
	v_permlane32_swap_b32_e32 v35, v37
	v_or_b32_e32 v34, v34, v36
	v_or_b32_e32 v35, v35, v37
	v_mov_b32_e32 v36, v34
	v_mov_b32_e32 v37, v35
	s_nop 1
	v_permlane16_swap_b32_e32 v34, v36
	v_permlane16_swap_b32_e32 v35, v37
	v_or_b32_e32 v34, v34, v36
	v_or_b32_e32 v35, v35, v37
	v_not_b32_e32 v34, v34
	v_not_b32_e32 v35, v35
	s_ashr_i32 s47, s46, 31
	s_and_saveexec_b64 s[0:1], s[16:17]
	v_lshl_add_u64 v[32:33], s[46:47], 3, v[2:3]
	global_store_dwordx2 v[32:33], v[34:35], off offset:128
	s_or_b64 exec, exec, s[0:1]
	s_and_b64 vcc, exec, s[6:7]
	s_cbranch_vccz .LBB0_1079

; __device__ __forceinline__ void sel_unit(LAS char* lds, int b, int u, const bf16_t* QI, const bf16_t* KIDX, const float* WIDX, unsigned long long* MASK) {
;     ...
;     for (int j = 0; j < 8; ++j) if (j < nj) {
;         const int t = SEL_TILE(j);
;         unsigned lo = 0u, hi = 0u;
; #pragma unroll
;         for (int kb = 0; kb < 4; ++kb)
; #pragma unroll
;             for (int i = 0; i < 4; ++i) { const unsigned k = sc[j][kb][i]; const unsigned kin = 16 * kb + 4 * kg2 + i;
;                 const unsigned v = 4095u - (unsigned)(64 * t + kin);
;                 const unsigned s = ((k > kstar) || (k == kstar && v >= vthr)) ? 1u : 0u;
;                 if (kb < 2) lo |= s << kin; else hi |= s << (kin - 32); __builtin_amdgcn_sched_barrier(0); }
;         { auto r = __builtin_amdgcn_permlane32_swap(lo, lo, false, false); lo = r[0] | r[1]; r = __builtin_amdgcn_permlane16_swap(lo, lo, false, false); lo = r[0] | r[1];
;           r = __builtin_amdgcn_permlane32_swap(hi, hi, false, false); hi = r[0] | r[1]; r = __builtin_amdgcn_permlane16_swap(hi, hi, false, false); hi = r[0] | r[1]; }
;         if (kg2 == 0) MASK[gq2 * 64 + t] = ((unsigned long long)hi << 32) | lo;
.LBB0_1092:
	s_lshl_b32 s21, s46, 6
	s_sub_i32 s21, 0x7ff, s21
	v_sub_u32_e32 v21, s21, v20
	v_sub_u32_e32 v21, v21, v0
	v_cmp_gt_i32_e64 vcc, 3, v21
	v_cmp_gt_i32_e64 s[0:1], 19, v21
	v_cmp_gt_i32_e64 s[18:19], 35, v21
	v_cmp_gt_i32_e64 s[22:23], 51, v21
	v_subb_co_u32_e64 v26, vcc, v127, v18, vcc
	v_subb_co_u32_e64 v27, s[0:1], v131, v18, s[0:1]
	v_subb_co_u32_e64 v28, s[18:19], v135, v18, s[18:19]
	v_subb_co_u32_e64 v29, s[22:23], v140, v18, s[22:23]
	v_addc_co_u32_e64 v22, vcc, 0, 0, vcc
	v_addc_co_u32_e64 v23, s[0:1], 0, 0, s[0:1]
	v_addc_co_u32_e64 v24, s[18:19], 0, 0, s[18:19]
	v_addc_co_u32_e64 v25, s[22:23], 0, 0, s[22:23]
	v_cmp_gt_i32_e64 vcc, 2, v21
	v_cmp_gt_i32_e64 s[0:1], 18, v21
	v_cmp_gt_i32_e64 s[18:19], 34, v21
	v_cmp_gt_i32_e64 s[22:23], 50, v21
	v_subb_co_u32_e64 v26, vcc, v128, v18, vcc
	v_subb_co_u32_e64 v27, s[0:1], v132, v18, s[0:1]
	v_subb_co_u32_e64 v28, s[18:19], v136, v18, s[18:19]
	v_subb_co_u32_e64 v29, s[22:23], v141, v18, s[22:23]
	v_addc_co_u32_e64 v22, vcc, v22, v22, vcc
	v_addc_co_u32_e64 v23, s[0:1], v23, v23, s[0:1]
	v_addc_co_u32_e64 v24, s[18:19], v24, v24, s[18:19]
	v_addc_co_u32_e64 v25, s[22:23], v25, v25, s[22:23]
	v_cmp_gt_i32_e64 vcc, 1, v21
	v_cmp_gt_i32_e64 s[0:1], 17, v21
	v_cmp_gt_i32_e64 s[18:19], 33, v21
	v_cmp_gt_i32_e64 s[22:23], 49, v21
	v_subb_co_u32_e64 v26, vcc, v125, v18, vcc
	v_subb_co_u32_e64 v27, s[0:1], v129, v18, s[0:1]
	v_subb_co_u32_e64 v28, s[18:19], v133, v18, s[18:19]
	v_subb_co_u32_e64 v29, s[22:23], v138, v18, s[22:23]
	v_addc_co_u32_e64 v22, vcc, v22, v22, vcc
	v_addc_co_u32_e64 v23, s[0:1], v23, v23, s[0:1]
	v_addc_co_u32_e64 v24, s[18:19], v24, v24, s[18:19]
	v_addc_co_u32_e64 v25, s[22:23], v25, v25, s[22:23]
	v_cmp_gt_i32_e64 vcc, 0, v21
	v_cmp_gt_i32_e64 s[0:1], 16, v21
	v_cmp_gt_i32_e64 s[18:19], 32, v21
	v_cmp_gt_i32_e64 s[22:23], 48, v21
	v_subb_co_u32_e64 v26, vcc, v126, v18, vcc
	v_subb_co_u32_e64 v27, s[0:1], v130, v18, s[0:1]
	v_subb_co_u32_e64 v28, s[18:19], v134, v18, s[18:19]
	v_subb_co_u32_e64 v29, s[22:23], v139, v18, s[22:23]
	v_addc_co_u32_e64 v22, vcc, v22, v22, vcc
	v_addc_co_u32_e64 v23, s[0:1], v23, v23, s[0:1]
	v_addc_co_u32_e64 v24, s[18:19], v24, v24, s[18:19]
	v_addc_co_u32_e64 v25, s[22:23], v25, v25, s[22:23]
	v_lshlrev_b32_e32 v34, v20, v22
	v_lshlrev_b32_e32 v35, v20, v24
	v_lshl_or_b32 v34, v23, v7, v34
	v_lshl_or_b32 v35, v25, v7, v35
	s_nop 0
	v_mov_b32_e32 v36, v34
	v_mov_b32_e32 v37, v35
	s_nop 1
	v_permlane32_swap_b32_e32 v34, v36
	v_permlane32_swap_b32_e32 v35, v37
	v_or_b32_e32 v34, v34, v36
	v_or_b32_e32 v35, v35, v37
	v_mov_b32_e32 v36, v34
	v_mov_b32_e32 v37, v35
	s_nop 1
	v_permlane16_swap_b32_e32 v34, v36
	v_permlane16_swap_b32_e32 v35, v37
	v_or_b32_e32 v34, v34, v36
	v_or_b32_e32 v35, v35, v37
	v_not_b32_e32 v34, v34
	v_not_b32_e32 v35, v35
	s_ashr_i32 s47, s46, 31
	s_and_saveexec_b64 s[0:1], s[16:17]
	v_lshl_add_u64 v[32:33], s[46:47], 3, v[2:3]
	global_store_dwordx2 v[32:33], v[34:35], off offset:256
	s_or_b64 exec, exec, s[0:1]
	s_and_b64 vcc, exec, s[10:11]
	s_cbranch_vccz .LBB0_1083

; __device__ __forceinline__ void sel_unit(LAS char* lds, int b, int u, const bf16_t* QI, const bf16_t* KIDX, const float* WIDX, unsigned long long* MASK) {
;     ...
;     for (int j = 0; j < 8; ++j) if (j < nj) {
;         const int t = SEL_TILE(j);
;         unsigned lo = 0u, hi = 0u;
; #pragma unroll
;         for (int kb = 0; kb < 4; ++kb)
; #pragma unroll
;             for (int i = 0; i < 4; ++i) { const unsigned k = sc[j][kb][i]; const unsigned kin = 16 * kb + 4 * kg2 + i;
;                 const unsigned v = 4095u - (unsigned)(64 * t + kin);
;                 const unsigned s = ((k > kstar) || (k == kstar && v >= vthr)) ? 1u : 0u;
;                 if (kb < 2) lo |= s << kin; else hi |= s << (kin - 32); __builtin_amdgcn_sched_barrier(0); }
;         { auto r = __builtin_amdgcn_permlane32_swap(lo, lo, false, false); lo = r[0] | r[1]; r = __builtin_amdgcn_permlane16_swap(lo, lo, false, false); lo = r[0] | r[1];
;           r = __builtin_amdgcn_permlane32_swap(hi, hi, false, false); hi = r[0] | r[1]; r = __builtin_amdgcn_permlane16_swap(hi, hi, false, false); hi = r[0] | r[1]; }
;         if (kg2 == 0) MASK[gq2 * 64 + t] = ((unsigned long long)hi << 32) | lo;
.LBB0_1096:
	s_lshl_b32 s21, s46, 6
	s_sub_i32 s21, 0x3ff, s21
	v_sub_u32_e32 v21, s21, v20
	v_sub_u32_e32 v21, v21, v0
	v_cmp_gt_i32_e64 vcc, 3, v21
	v_cmp_gt_i32_e64 s[0:1], 19, v21
	v_cmp_gt_i32_e64 s[18:19], 35, v21
	v_cmp_gt_i32_e64 s[22:23], 51, v21
	v_subb_co_u32_e64 v26, vcc, v193, v18, vcc
	v_subb_co_u32_e64 v27, s[0:1], v197, v18, s[0:1]
	v_subb_co_u32_e64 v28, s[18:19], v54, v18, s[18:19]
	v_subb_co_u32_e64 v29, s[22:23], v219, v18, s[22:23]
	v_addc_co_u32_e64 v22, vcc, 0, 0, vcc
	v_addc_co_u32_e64 v23, s[0:1], 0, 0, s[0:1]
	v_addc_co_u32_e64 v24, s[18:19], 0, 0, s[18:19]
	v_addc_co_u32_e64 v25, s[22:23], 0, 0, s[22:23]
	v_cmp_gt_i32_e64 vcc, 2, v21
	v_cmp_gt_i32_e64 s[0:1], 18, v21
	v_cmp_gt_i32_e64 s[18:19], 34, v21
	v_cmp_gt_i32_e64 s[22:23], 50, v21
	v_subb_co_u32_e64 v26, vcc, v194, v18, vcc
	v_subb_co_u32_e64 v27, s[0:1], v198, v18, s[0:1]
	v_subb_co_u32_e64 v28, s[18:19], v55, v18, s[18:19]
	v_subb_co_u32_e64 v29, s[22:23], v220, v18, s[22:23]
	v_addc_co_u32_e64 v22, vcc, v22, v22, vcc
	v_addc_co_u32_e64 v23, s[0:1], v23, v23, s[0:1]
	v_addc_co_u32_e64 v24, s[18:19], v24, v24, s[18:19]
	v_addc_co_u32_e64 v25, s[22:23], v25, v25, s[22:23]
	v_cmp_gt_i32_e64 vcc, 1, v21
	v_cmp_gt_i32_e64 s[0:1], 17, v21
	v_cmp_gt_i32_e64 s[18:19], 33, v21
	v_cmp_gt_i32_e64 s[22:23], 49, v21
	v_subb_co_u32_e64 v26, vcc, v191, v18, vcc
	v_subb_co_u32_e64 v27, s[0:1], v195, v18, s[0:1]
	v_subb_co_u32_e64 v28, s[18:19], v56, v18, s[18:19]
	v_subb_co_u32_e64 v29, s[22:23], v199, v18, s[22:23]
	v_addc_co_u32_e64 v22, vcc, v22, v22, vcc
	v_addc_co_u32_e64 v23, s[0:1], v23, v23, s[0:1]
	v_addc_co_u32_e64 v24, s[18:19], v24, v24, s[18:19]
	v_addc_co_u32_e64 v25, s[22:23], v25, v25, s[22:23]
	v_cmp_gt_i32_e64 vcc, 0, v21
	v_cmp_gt_i32_e64 s[0:1], 16, v21
	v_cmp_gt_i32_e64 s[18:19], 32, v21
	v_cmp_gt_i32_e64 s[22:23], 48, v21
	v_subb_co_u32_e64 v26, vcc, v192, v18, vcc
	v_subb_co_u32_e64 v27, s[0:1], v196, v18, s[0:1]
	v_subb_co_u32_e64 v28, s[18:19], v57, v18, s[18:19]
	v_subb_co_u32_e64 v29, s[22:23], v218, v18, s[22:23]
	v_addc_co_u32_e64 v22, vcc, v22, v22, vcc
	v_addc_co_u32_e64 v23, s[0:1], v23, v23, s[0:1]
	v_addc_co_u32_e64 v24, s[18:19], v24, v24, s[18:19]
	v_addc_co_u32_e64 v25, s[22:23], v25, v25, s[22:23]
	v_lshlrev_b32_e32 v34, v20, v22
	v_lshlrev_b32_e32 v35, v20, v24
	v_lshl_or_b32 v34, v23, v7, v34
	v_lshl_or_b32 v35, v25, v7, v35
	s_nop 0
	v_mov_b32_e32 v36, v34
	v_mov_b32_e32 v37, v35
	s_nop 1
	v_permlane32_swap_b32_e32 v34, v36
	v_permlane32_swap_b32_e32 v35, v37
	v_or_b32_e32 v34, v34, v36
	v_or_b32_e32 v35, v35, v37
	v_mov_b32_e32 v36, v34
	v_mov_b32_e32 v37, v35
	s_nop 1
	v_permlane16_swap_b32_e32 v34, v36
	v_permlane16_swap_b32_e32 v35, v37
	v_or_b32_e32 v34, v34, v36
	v_or_b32_e32 v35, v35, v37
	v_not_b32_e32 v34, v34
	v_not_b32_e32 v35, v35
	s_ashr_i32 s47, s46, 31
	s_and_saveexec_b64 s[0:1], s[16:17]
	v_lshl_add_u64 v[32:33], s[46:47], 3, v[2:3]
	global_store_dwordx2 v[32:33], v[34:35], off offset:384
	s_or_b64 exec, exec, s[0:1]
	s_and_b64 vcc, exec, s[14:15]
	s_cbranch_vccnz .LBB0_1102
.LBB0_1099:
	s_lshl_b32 s21, s46, 6
	s_sub_i32 s21, 0x1ff, s21
	v_sub_u32_e32 v21, s21, v20
	v_sub_u32_e32 v21, v21, v0
	v_cmp_gt_i32_e64 vcc, 3, v21
	v_cmp_gt_i32_e64 s[0:1], 19, v21
	v_cmp_gt_i32_e64 s[18:19], 35, v21
	v_cmp_gt_i32_e64 s[22:23], 51, v21
	v_subb_co_u32_e64 v26, vcc, v223, v18, vcc
	v_subb_co_u32_e64 v27, s[0:1], v227, v18, s[0:1]
	v_subb_co_u32_e64 v28, s[18:19], v12, v18, s[18:19]
	v_subb_co_u32_e64 v29, s[22:23], v16, v18, s[22:23]
	v_addc_co_u32_e64 v22, vcc, 0, 0, vcc
	v_addc_co_u32_e64 v23, s[0:1], 0, 0, s[0:1]
	v_addc_co_u32_e64 v24, s[18:19], 0, 0, s[18:19]
	v_addc_co_u32_e64 v25, s[22:23], 0, 0, s[22:23]
	v_cmp_gt_i32_e64 vcc, 2, v21
	v_cmp_gt_i32_e64 s[0:1], 18, v21
	v_cmp_gt_i32_e64 s[18:19], 34, v21
	v_cmp_gt_i32_e64 s[22:23], 50, v21
	v_subb_co_u32_e64 v26, vcc, v224, v18, vcc
	v_subb_co_u32_e64 v27, s[0:1], v228, v18, s[0:1]
	v_subb_co_u32_e64 v28, s[18:19], v13, v18, s[18:19]
	v_subb_co_u32_e64 v29, s[22:23], v17, v18, s[22:23]
	v_addc_co_u32_e64 v22, vcc, v22, v22, vcc
	v_addc_co_u32_e64 v23, s[0:1], v23, v23, s[0:1]
	v_addc_co_u32_e64 v24, s[18:19], v24, v24, s[18:19]
	v_addc_co_u32_e64 v25, s[22:23], v25, v25, s[22:23]
	v_cmp_gt_i32_e64 vcc, 1, v21
	v_cmp_gt_i32_e64 s[0:1], 17, v21
	v_cmp_gt_i32_e64 s[18:19], 33, v21
	v_cmp_gt_i32_e64 s[22:23], 49, v21
	v_subb_co_u32_e64 v26, vcc, v221, v18, vcc
	v_subb_co_u32_e64 v27, s[0:1], v225, v18, s[0:1]
	v_subb_co_u32_e64 v28, s[18:19], v10, v18, s[18:19]
	v_subb_co_u32_e64 v29, s[22:23], v14, v18, s[22:23]
	v_addc_co_u32_e64 v22, vcc, v22, v22, vcc
	v_addc_co_u32_e64 v23, s[0:1], v23, v23, s[0:1]
	v_addc_co_u32_e64 v24, s[18:19], v24, v24, s[18:19]
	v_addc_co_u32_e64 v25, s[22:23], v25, v25, s[22:23]
	v_cmp_gt_i32_e64 vcc, 0, v21
	v_cmp_gt_i32_e64 s[0:1], 16, v21
	v_cmp_gt_i32_e64 s[18:19], 32, v21
	v_cmp_gt_i32_e64 s[22:23], 48, v21
	v_subb_co_u32_e64 v26, vcc, v222, v18, vcc
	v_subb_co_u32_e64 v27, s[0:1], v226, v18, s[0:1]
	v_subb_co_u32_e64 v28, s[18:19], v11, v18, s[18:19]
	v_subb_co_u32_e64 v29, s[22:23], v15, v18, s[22:23]
	v_addc_co_u32_e64 v22, vcc, v22, v22, vcc
	v_addc_co_u32_e64 v23, s[0:1], v23, v23, s[0:1]
	v_addc_co_u32_e64 v24, s[18:19], v24, v24, s[18:19]
	v_addc_co_u32_e64 v25, s[22:23], v25, v25, s[22:23]
	v_lshlrev_b32_e32 v34, v20, v22
	v_lshlrev_b32_e32 v35, v20, v24
	v_lshl_or_b32 v34, v23, v7, v34
	v_lshl_or_b32 v35, v25, v7, v35
	s_nop 0
	v_mov_b32_e32 v36, v34
	v_mov_b32_e32 v37, v35
	s_nop 1
	v_permlane32_swap_b32_e32 v34, v36
	v_permlane32_swap_b32_e32 v35, v37
	v_or_b32_e32 v34, v34, v36
	v_or_b32_e32 v35, v35, v37
	v_mov_b32_e32 v36, v34
	v_mov_b32_e32 v37, v35
	s_nop 1
	v_permlane16_swap_b32_e32 v34, v36
	v_permlane16_swap_b32_e32 v35, v37
	v_or_b32_e32 v34, v34, v36
	v_or_b32_e32 v35, v35, v37
	v_not_b32_e32 v34, v34
	v_not_b32_e32 v35, v35
	s_ashr_i32 s47, s46, 31
	s_and_saveexec_b64 s[0:1], s[16:17]
	v_lshl_add_u64 v[32:33], s[46:47], 3, v[2:3]
	global_store_dwordx2 v[32:33], v[34:35], off offset:448
	s_or_b64 exec, exec, s[0:1]
